# merge K-loop: global loads issued two K-tiles ahead (second staging register set in free VGPRs, loop unrolled by two, counted vmcnt)
# baseline (speedup 1.0000x reference)
; DI int tidx() { int t = threadIdx.x & 255; asm volatile("" : "+v"(t)); return t; }
; #define GEMM_STAGE(D_) do { unsigned char* d_ = (D_); \
;         *(u32x4*)(d_) = ra0; *(u32x4*)(d_ + OPB) = rb0; *(u32x4*)(d_ + PASSB) = ra1; *(u32x4*)(d_ + OPB + PASSB) = rb1; \
;         if constexpr (NJ == 4) { *(u32x4*)(d_ + 2 * PASSB) = ra2; *(u32x4*)(d_ + OPB + 2 * PASSB) = rb2; *(u32x4*)(d_ + 3 * PASSB) = ra3; *(u32x4*)(d_ + OPB + 3 * PASSB) = rb3; } } while (0)
; template <int BK>
; DI void gemm_mainloop(const bf16_t* A, int lda, const bf16_t* B, int ldb, int K, f32x16 (&acc)[2][2], unsigned char* smem) {
;     ...
;     const int tid = tidx(), lane = tid & 63, w = tid >> 6, wm = w >> 1, wn = w & 1, r = lane & 31, hh = lane >> 5;
;     const int lrow = tid / CPR, lcol = (tid % CPR) * 8;
;     const bf16_t* ap = A + (size_t)lrow * lda + lcol;
;     const bf16_t* bp = B + (size_t)lrow * ldb + lcol;
;     const size_t astep = (size_t)RPP * lda, bstep = (size_t)RPP * ldb;
;     const int st_off = lrow * ROWB + (tid % CPR) * 16;
;     u32x4 ra0, ra1, ra2, ra3, rb0, rb1, rb2, rb3;
;     ra0 = *(const u32x4*)(ap); rb0 = *(const u32x4*)(bp);
;     ra1 = *(const u32x4*)(ap + astep); rb1 = *(const u32x4*)(bp + bstep);
;     if constexpr (NJ == 4) { ra2 = *(const u32x4*)(ap + 2 * astep); rb2 = *(const u32x4*)(bp + 2 * bstep); ra3 = *(const u32x4*)(ap + 3 * astep); rb3 = *(const u32x4*)(bp + 3 * bstep); }
;     else { ra2 = ra0; ra3 = ra0; rb2 = rb0; rb3 = rb0; }
;     ...
;     GEMM_STAGE(smem + st_off);
;     __syncthreads();
; DI void phase_merge(KargPtr p, int l, unsigned char* smem) {
;     ...
;         for (int br = 0; br < 3; ++br) {
;             f32x16 acc[2][2]; zero_acc(acc);
;             const bf16_t* Y = (br == 0 ? p->qf : br == 1 ? p->qn : p->qs) + (size_t)m0 * 512;
;             const bf16_t* WO = WL + (br == 0 ? W_OF : br == 1 ? W_OM : W_OS) + (size_t)nt * 128 * 512;
;             gemm_mainloop<64>(WO, 512, Y, 512, 512, acc, smem);
.LBB0_555:
	s_cmp_lg_u32 s5, 0
	s_cselect_b64 s[12:13], -1, 0
	s_cmp_eq_u32 s5, 1
	s_movk_i32 s14, 0x128
	s_mov_b32 s15, 0x7e8000
	s_cselect_b32 s14, s14, 0xf8
	s_cselect_b32 s15, s15, 0x868000
	s_cmp_eq_u32 s5, 0
	s_cselect_b32 s14, 0xe0, s14
	s_cselect_b32 s19, 0x768000, s15
	s_add_u32 s14, s0, s14
	s_addc_u32 s15, s1, 0
	s_load_dwordx2 s[14:15], s[14:15], 0x0
	v_mov_b32_e32 v48, v199
	v_mov_b32_e32 v10, v167
	v_ashrrev_i32_e32 v4, 31, v48
	v_lshrrev_b32_e32 v4, 29, v4
	v_add_u32_e32 v4, v48, v4
	s_waitcnt lgkmcnt(0)
	s_add_u32 s14, s14, s10
	v_ashrrev_i32_e32 v46, 3, v4
	v_and_b32_e32 v4, -8, v4
	s_addc_u32 s15, s15, s11
	s_lshl_b32 s19, s19, 1
	v_sub_u32_e32 v49, v48, v4
	s_add_u32 s20, s17, s19
	v_lshlrev_b32_e32 v4, 3, v49
	v_ashrrev_i32_e32 v47, 31, v46
	s_addc_u32 s21, s18, 0
	v_lshlrev_b64 v[6:7], 10, v[46:47]
	v_ashrrev_i32_e32 v5, 31, v4
	v_lshl_add_u64 v[8:9], s[20:21], 0, v[6:7]
	v_lshlrev_b64 v[4:5], 1, v[4:5]
	v_lshl_add_u64 v[134:135], v[8:9], 0, v[4:5]
	v_lshl_add_u64 v[6:7], s[14:15], 0, v[6:7]
	v_lshl_add_u64 v[136:137], v[6:7], 0, v[4:5]
	v_add_co_u32_e32 v4, vcc, s69, v134
	global_load_dwordx4 v[14:17], v[134:135], off
	global_load_dwordx4 v[18:21], v[136:137], off
	v_addc_co_u32_e32 v5, vcc, 0, v135, vcc
	global_load_dwordx4 v[22:25], v[4:5], off
	v_add_co_u32_e32 v4, vcc, s69, v136
	v_and_b32_e32 v47, 31, v48
	s_nop 0
	v_addc_co_u32_e32 v5, vcc, 0, v137, vcc
	global_load_dwordx4 v[26:29], v[4:5], off
	v_add_co_u32_e32 v4, vcc, s65, v134
	v_lshrrev_b32_e32 v50, 1, v48
	s_nop 0
	v_addc_co_u32_e32 v5, vcc, 0, v135, vcc
	global_load_dwordx4 v[30:33], v[4:5], off
	v_add_co_u32_e32 v4, vcc, s65, v136
	s_mov_b32 s20, 0xfffffc0
	s_nop 0
	v_addc_co_u32_e32 v5, vcc, 0, v137, vcc
	global_load_dwordx4 v[34:37], v[4:5], off
	v_add_co_u32_e32 v4, vcc, s67, v136
	v_and_b32_e32 v51, 0x5f, v48
	s_nop 0
	v_addc_co_u32_e32 v5, vcc, 0, v137, vcc
	global_load_dwordx4 v[38:41], v[4:5], off
	v_add_co_u32_e32 v4, vcc, s67, v134
	v_and_or_b32 v47, v50, s20, v47
	s_nop 0
	v_addc_co_u32_e32 v5, vcc, 0, v135, vcc
	global_load_dwordx4 v[42:45], v[4:5], off
	v_lshl_add_u64 v[146:147], v[134:135], 0, 0
	v_lshl_add_u64 v[148:149], v[136:137], 0, 0
	v_lshl_add_u64 v[138:139], v[146:147], 0, s[92:93]
	v_lshl_add_u64 v[142:143], v[148:149], 0, s[92:93]
	v_lshl_add_u64 v[150:151], v[146:147], 0, s[80:81]
	v_lshl_add_u64 v[158:159], v[148:149], 0, s[80:81]
	v_lshl_add_u64 v[162:163], v[146:147], 0, s[40:41]
	v_lshl_add_u64 v[168:169], v[148:149], 0, s[40:41]
	v_lshl_add_u64 v[146:147], v[146:147], 0, s[94:95]
	global_load_dwordx4 v[138:141], v[138:139], off
	global_load_dwordx4 v[142:145], v[142:143], off
	global_load_dwordx4 v[150:153], v[150:151], off
	global_load_dwordx4 v[158:161], v[158:159], off
	global_load_dwordx4 v[162:165], v[162:163], off
	global_load_dwordx4 v[168:171], v[168:169], off
	global_load_dwordx4 v[172:175], v[146:147], off
	v_lshl_add_u64 v[146:147], v[148:149], 0, s[94:95]
	global_load_dwordx4 v[176:179], v[146:147], off
	v_and_b32_e32 v48, 16, v50
	v_mad_u64_u32 v[154:155], s[20:21], v47, s74, v[48:49]
	v_mul_lo_u32 v46, v46, s74
	v_lshlrev_b32_e32 v47, 4, v49
	v_add3_u32 v156, s3, v46, v47
	s_mov_b64 s[14:15], 0
	s_mov_b32 s19, 0
	v_mov_b32_e32 v4, 0
	v_mov_b32_e32 v5, v167
	v_mov_b32_e32 v6, v167
	v_mov_b32_e32 v7, v167
	v_mov_b32_e32 v8, v167
	v_mov_b32_e32 v9, v167
	v_mov_b32_e32 v11, v167
	v_mov_b32_e32 v12, v167
	v_mov_b32_e32 v13, v167
	v_mad_u32_u24 v155, v51, s74, v48
	v_mov_b32_e32 v46, v167
	v_mov_b32_e32 v47, v167
	v_mov_b32_e32 v48, v167
	v_mov_b32_e32 v49, v167
	v_mov_b32_e32 v50, v167
	v_mov_b32_e32 v51, v167
	v_mov_b32_e32 v52, 0
	v_mov_b32_e32 v53, v167
	v_mov_b32_e32 v54, v167
	v_mov_b32_e32 v55, v167
	v_mov_b32_e32 v56, v167
	v_mov_b32_e32 v57, v167
	v_mov_b32_e32 v58, v167
	s_waitcnt vmcnt(14)
	ds_write_b128 v156, v[18:21] offset:18432
	ds_write_b128 v156, v[14:17]
	s_waitcnt vmcnt(12)
	ds_write_b128 v156, v[26:29] offset:23040
	s_waitcnt vmcnt(10)
	ds_write_b128 v156, v[34:37] offset:27648
	s_waitcnt vmcnt(9)
	ds_write_b128 v156, v[38:41] offset:32256
	ds_write_b128 v156, v[22:25] offset:4608
	ds_write_b128 v156, v[30:33] offset:9216
	s_waitcnt vmcnt(8)
	ds_write_b128 v156, v[42:45] offset:13824
	v_mov_b32_e32 v14, v167
	v_mov_b32_e32 v15, v167
	v_mov_b32_e32 v16, v167
	v_mov_b32_e32 v17, v167
	v_mov_b32_e32 v18, v167
	v_mov_b32_e32 v19, v167
	v_mov_b32_e32 v20, 0
	v_mov_b32_e32 v21, v167
	v_mov_b32_e32 v22, v167
	v_mov_b32_e32 v23, v167
	v_mov_b32_e32 v24, v167
	v_mov_b32_e32 v25, v167
	v_mov_b32_e32 v26, v167
	v_mov_b32_e32 v27, v167
	v_mov_b32_e32 v28, v167
	v_mov_b32_e32 v29, v167
	v_mov_b32_e32 v30, v167
	v_mov_b32_e32 v31, v167
	v_mov_b32_e32 v32, v167
	v_mov_b32_e32 v33, v167
	v_mov_b32_e32 v34, v167
	v_mov_b32_e32 v35, v167
	v_mov_b32_e32 v36, 0
	v_mov_b32_e32 v37, v167
	v_mov_b32_e32 v38, v167
	v_mov_b32_e32 v39, v167
	v_mov_b32_e32 v40, v167
	v_mov_b32_e32 v41, v167
	v_mov_b32_e32 v42, v167
	v_mov_b32_e32 v43, v167
	v_mov_b32_e32 v44, v167
	v_mov_b32_e32 v45, v167
	v_mov_b32_e32 v59, v167
	v_mov_b32_e32 v60, v167
	v_mov_b32_e32 v61, v167
	v_mov_b32_e32 v62, v167
	v_mov_b32_e32 v63, v167
	v_mov_b32_e32 v64, v167
	v_mov_b32_e32 v65, v167
	v_mov_b32_e32 v66, v167
	v_mov_b32_e32 v67, v167
	s_waitcnt lgkmcnt(0)
	s_barrier
; #define GLOAD16(dst, ptr) asm volatile("global_load_dwordx4 %0, %1, off" : "=v"(dst) : "v"(ptr))
; #define GEMM_STAGE(D_) do { unsigned char* d_ = (D_); \
;         *(u32x4*)(d_) = ra0; *(u32x4*)(d_ + OPB) = rb0; *(u32x4*)(d_ + PASSB) = ra1; *(u32x4*)(d_ + OPB + PASSB) = rb1; \
;         if constexpr (NJ == 4) { *(u32x4*)(d_ + 2 * PASSB) = ra2; *(u32x4*)(d_ + OPB + 2 * PASSB) = rb2; *(u32x4*)(d_ + 3 * PASSB) = ra3; *(u32x4*)(d_ + OPB + 3 * PASSB) = rb3; } } while (0)
; template <int BK>
; DI void gemm_mainloop(const bf16_t* A, int lda, const bf16_t* B, int ldb, int K, f32x16 (&acc)[2][2], unsigned char* smem) {
;     ...
;     for (int kt = 0; kt < nk - 1; ++kt) {
;         const int buf = kt & 1;
;         ap += BK; bp += BK;
;         GLOAD16(ra0, ap); GLOAD16(rb0, bp); GLOAD16(ra1, ap + astep); GLOAD16(rb1, bp + bstep);
;         if constexpr (NJ == 4) { GLOAD16(ra2, ap + 2 * astep); GLOAD16(rb2, bp + 2 * bstep); GLOAD16(ra3, ap + 3 * astep); GLOAD16(rb3, bp + 3 * bstep); }
;         __builtin_amdgcn_sched_barrier(0);
;         GEMM_COMPUTE(buf);
;         __builtin_amdgcn_sched_barrier(0);
;         if constexpr (NJ == 4) asm volatile("s_waitcnt vmcnt(0)" : "+v"(ra0), "+v"(rb0), "+v"(ra1), "+v"(rb1), "+v"(ra2), "+v"(rb2), "+v"(ra3), "+v"(rb3));
;         else asm volatile("s_waitcnt vmcnt(0)" : "+v"(ra0), "+v"(rb0), "+v"(ra1), "+v"(rb1));
;         GEMM_STAGE(smem + (buf ^ 1) * STB + st_off);
;         __syncthreads();
;     }
.LBB0_556:
	v_lshl_add_u64 v[146:147], v[134:135], 0, s[14:15]
	v_lshl_add_u64 v[148:149], v[136:137], 0, s[14:15]
	v_lshl_add_u64 v[146:147], v[146:147], 0, s[92:93]
	v_lshl_add_u64 v[148:149], v[148:149], 0, s[92:93]
	v_lshl_add_u64 v[222:223], v[146:147], 0, s[92:93]
	v_lshl_add_u64 v[226:227], v[148:149], 0, s[92:93]
	v_lshl_add_u64 v[230:231], v[146:147], 0, s[80:81]
	v_lshl_add_u64 v[234:235], v[148:149], 0, s[80:81]
	v_lshl_add_u64 v[238:239], v[146:147], 0, s[40:41]
	v_lshl_add_u64 v[242:243], v[148:149], 0, s[40:41]
	v_lshl_add_u64 v[146:147], v[146:147], 0, s[94:95]
	global_load_dwordx4 v[222:225], v[222:223], off
	global_load_dwordx4 v[226:229], v[226:227], off
	global_load_dwordx4 v[230:233], v[230:231], off
	global_load_dwordx4 v[234:237], v[234:235], off
	global_load_dwordx4 v[238:241], v[238:239], off
	global_load_dwordx4 v[242:245], v[242:243], off
	global_load_dwordx4 v[246:249], v[146:147], off
	v_lshl_add_u64 v[146:147], v[148:149], 0, s[94:95]
	global_load_dwordx4 v[250:253], v[146:147], off
	s_and_b32 s20, s19, 1
	s_mul_i32 s21, s20, 0x9000
	s_add_i32 s21, s3, s21
	v_add_u32_e32 v146, s21, v154
	v_add_u32_e32 v147, s21, v155
	ds_read_b128 v[180:183], v146
	ds_read_b128 v[184:187], v146 offset:32
	ds_read_b128 v[188:191], v146 offset:4608
	ds_read_b128 v[192:195], v146 offset:4640
	ds_read_b128 v[200:203], v147 offset:18432
	ds_read_b128 v[210:213], v147 offset:18464
	ds_read_b128 v[214:217], v147 offset:23040
	ds_read_b128 v[218:221], v147 offset:23072
	s_waitcnt lgkmcnt(3)
	v_mfma_f32_32x32x16_bf16 v[52:67], v[180:183], v[200:203], v[52:67]
	s_waitcnt lgkmcnt(1)
	v_mfma_f32_32x32x16_bf16 v[36:51], v[180:183], v[214:217], v[36:51]
	v_mfma_f32_32x32x16_bf16 v[20:35], v[188:191], v[200:203], v[20:35]
	v_mfma_f32_32x32x16_bf16 v[4:19], v[188:191], v[214:217], v[4:19]
	ds_read_b128 v[180:183], v146 offset:64
	ds_read_b128 v[188:191], v146 offset:4672
	ds_read_b128 v[200:203], v147 offset:18496
	ds_read_b128 v[214:217], v147 offset:23104
	v_mfma_f32_32x32x16_bf16 v[52:67], v[184:187], v[210:213], v[52:67]
	s_waitcnt lgkmcnt(4)
	v_mfma_f32_32x32x16_bf16 v[36:51], v[184:187], v[218:221], v[36:51]
	v_mfma_f32_32x32x16_bf16 v[20:35], v[192:195], v[210:213], v[20:35]
	v_mfma_f32_32x32x16_bf16 v[4:19], v[192:195], v[218:221], v[4:19]
	ds_read_b128 v[184:187], v146 offset:96
	ds_read_b128 v[192:195], v146 offset:4704
	ds_read_b128 v[210:213], v147 offset:18528
	ds_read_b128 v[218:221], v147 offset:23136
	s_waitcnt lgkmcnt(5)
	v_mfma_f32_32x32x16_bf16 v[52:67], v[180:183], v[200:203], v[52:67]
	s_waitcnt lgkmcnt(4)
	v_mfma_f32_32x32x16_bf16 v[36:51], v[180:183], v[214:217], v[36:51]
	v_mfma_f32_32x32x16_bf16 v[20:35], v[188:191], v[200:203], v[20:35]
	v_mfma_f32_32x32x16_bf16 v[4:19], v[188:191], v[214:217], v[4:19]
	s_waitcnt lgkmcnt(1)
	v_mfma_f32_32x32x16_bf16 v[52:67], v[184:187], v[210:213], v[52:67]
	s_waitcnt lgkmcnt(0)
	v_mfma_f32_32x32x16_bf16 v[36:51], v[184:187], v[218:221], v[36:51]
	v_mfma_f32_32x32x16_bf16 v[20:35], v[192:195], v[210:213], v[20:35]
	v_mfma_f32_32x32x16_bf16 v[4:19], v[192:195], v[218:221], v[4:19]
	s_xor_b32 s20, s20, 1
	s_add_i32 s19, s19, 1
	s_add_u32 s14, s14, 0x80
	s_mul_i32 s20, s20, 0x9000
	s_addc_u32 s15, s15, 0
	s_barrier
	s_waitcnt vmcnt(8)
	v_add_u32_e32 v146, s20, v156
	ds_write_b128 v146, v[138:141]
	ds_write_b128 v146, v[142:145] offset:18432
	ds_write_b128 v146, v[150:153] offset:4608
	ds_write_b128 v146, v[158:161] offset:23040
	ds_write_b128 v146, v[162:165] offset:9216
	ds_write_b128 v146, v[168:171] offset:27648
	ds_write_b128 v146, v[172:175] offset:13824
	ds_write_b128 v146, v[176:179] offset:32256
	s_waitcnt lgkmcnt(0)
	s_barrier
	v_lshl_add_u64 v[146:147], v[134:135], 0, s[14:15]
	v_lshl_add_u64 v[148:149], v[136:137], 0, s[14:15]
	v_lshl_add_u64 v[146:147], v[146:147], 0, s[92:93]
	v_lshl_add_u64 v[148:149], v[148:149], 0, s[92:93]
	v_lshl_add_u64 v[138:139], v[146:147], 0, s[92:93]
	v_lshl_add_u64 v[142:143], v[148:149], 0, s[92:93]
	v_lshl_add_u64 v[150:151], v[146:147], 0, s[80:81]
	v_lshl_add_u64 v[158:159], v[148:149], 0, s[80:81]
	v_lshl_add_u64 v[162:163], v[146:147], 0, s[40:41]
	v_lshl_add_u64 v[168:169], v[148:149], 0, s[40:41]
	v_lshl_add_u64 v[146:147], v[146:147], 0, s[94:95]
	global_load_dwordx4 v[138:141], v[138:139], off
	global_load_dwordx4 v[142:145], v[142:143], off
	global_load_dwordx4 v[150:153], v[150:151], off
	global_load_dwordx4 v[158:161], v[158:159], off
	global_load_dwordx4 v[162:165], v[162:163], off
	global_load_dwordx4 v[168:171], v[168:169], off
	global_load_dwordx4 v[172:175], v[146:147], off
	v_lshl_add_u64 v[146:147], v[148:149], 0, s[94:95]
	global_load_dwordx4 v[176:179], v[146:147], off
	s_and_b32 s20, s19, 1
	s_mul_i32 s21, s20, 0x9000
	s_add_i32 s21, s3, s21
	v_add_u32_e32 v146, s21, v154
	v_add_u32_e32 v147, s21, v155
	ds_read_b128 v[180:183], v146
	ds_read_b128 v[184:187], v146 offset:32
	ds_read_b128 v[188:191], v146 offset:4608
	ds_read_b128 v[192:195], v146 offset:4640
	ds_read_b128 v[200:203], v147 offset:18432
	ds_read_b128 v[210:213], v147 offset:18464
	ds_read_b128 v[214:217], v147 offset:23040
	ds_read_b128 v[218:221], v147 offset:23072
	s_waitcnt lgkmcnt(3)
	v_mfma_f32_32x32x16_bf16 v[52:67], v[180:183], v[200:203], v[52:67]
	s_waitcnt lgkmcnt(1)
	v_mfma_f32_32x32x16_bf16 v[36:51], v[180:183], v[214:217], v[36:51]
	v_mfma_f32_32x32x16_bf16 v[20:35], v[188:191], v[200:203], v[20:35]
	v_mfma_f32_32x32x16_bf16 v[4:19], v[188:191], v[214:217], v[4:19]
	ds_read_b128 v[180:183], v146 offset:64
	ds_read_b128 v[188:191], v146 offset:4672
	ds_read_b128 v[200:203], v147 offset:18496
	ds_read_b128 v[214:217], v147 offset:23104
	v_mfma_f32_32x32x16_bf16 v[52:67], v[184:187], v[210:213], v[52:67]
	s_waitcnt lgkmcnt(4)
	v_mfma_f32_32x32x16_bf16 v[36:51], v[184:187], v[218:221], v[36:51]
	v_mfma_f32_32x32x16_bf16 v[20:35], v[192:195], v[210:213], v[20:35]
	v_mfma_f32_32x32x16_bf16 v[4:19], v[192:195], v[218:221], v[4:19]
	ds_read_b128 v[184:187], v146 offset:96
	ds_read_b128 v[192:195], v146 offset:4704
	ds_read_b128 v[210:213], v147 offset:18528
	ds_read_b128 v[218:221], v147 offset:23136
	s_waitcnt lgkmcnt(5)
	v_mfma_f32_32x32x16_bf16 v[52:67], v[180:183], v[200:203], v[52:67]
	s_waitcnt lgkmcnt(4)
	v_mfma_f32_32x32x16_bf16 v[36:51], v[180:183], v[214:217], v[36:51]
	v_mfma_f32_32x32x16_bf16 v[20:35], v[188:191], v[200:203], v[20:35]
	v_mfma_f32_32x32x16_bf16 v[4:19], v[188:191], v[214:217], v[4:19]
	s_waitcnt lgkmcnt(1)
	v_mfma_f32_32x32x16_bf16 v[52:67], v[184:187], v[210:213], v[52:67]
	s_waitcnt lgkmcnt(0)
	v_mfma_f32_32x32x16_bf16 v[36:51], v[184:187], v[218:221], v[36:51]
	v_mfma_f32_32x32x16_bf16 v[20:35], v[192:195], v[210:213], v[20:35]
	v_mfma_f32_32x32x16_bf16 v[4:19], v[192:195], v[218:221], v[4:19]
	s_xor_b32 s20, s20, 1
	s_add_i32 s19, s19, 1
	s_add_u32 s14, s14, 0x80
	s_mul_i32 s20, s20, 0x9000
	s_addc_u32 s15, s15, 0
	s_barrier
; #define GLOAD16(dst, ptr) asm volatile("global_load_dwordx4 %0, %1, off" : "=v"(dst) : "v"(ptr))
; #define GEMM_STAGE(D_) do { unsigned char* d_ = (D_); \
;         *(u32x4*)(d_) = ra0; *(u32x4*)(d_ + OPB) = rb0; *(u32x4*)(d_ + PASSB) = ra1; *(u32x4*)(d_ + OPB + PASSB) = rb1; \
;         if constexpr (NJ == 4) { *(u32x4*)(d_ + 2 * PASSB) = ra2; *(u32x4*)(d_ + OPB + 2 * PASSB) = rb2; *(u32x4*)(d_ + 3 * PASSB) = ra3; *(u32x4*)(d_ + OPB + 3 * PASSB) = rb3; } } while (0)
; template <int BK>
; DI void gemm_mainloop(const bf16_t* A, int lda, const bf16_t* B, int ldb, int K, f32x16 (&acc)[2][2], unsigned char* smem) {
;     ...
;     for (int kt = 0; kt < nk - 1; ++kt) {
;         const int buf = kt & 1;
;         ap += BK; bp += BK;
;         GLOAD16(ra0, ap); GLOAD16(rb0, bp); GLOAD16(ra1, ap + astep); GLOAD16(rb1, bp + bstep);
;         if constexpr (NJ == 4) { GLOAD16(ra2, ap + 2 * astep); GLOAD16(rb2, bp + 2 * bstep); GLOAD16(ra3, ap + 3 * astep); GLOAD16(rb3, bp + 3 * bstep); }
;         __builtin_amdgcn_sched_barrier(0);
;         GEMM_COMPUTE(buf);
;         __builtin_amdgcn_sched_barrier(0);
;         if constexpr (NJ == 4) asm volatile("s_waitcnt vmcnt(0)" : "+v"(ra0), "+v"(rb0), "+v"(ra1), "+v"(rb1), "+v"(ra2), "+v"(rb2), "+v"(ra3), "+v"(rb3));
;         else asm volatile("s_waitcnt vmcnt(0)" : "+v"(ra0), "+v"(rb0), "+v"(ra1), "+v"(rb1));
;         GEMM_STAGE(smem + (buf ^ 1) * STB + st_off);
;         __syncthreads();
;     }
;     GEMM_COMPUTE((nk - 1) & 1);
;     __syncthreads();
	s_waitcnt vmcnt(8)
	v_add_u32_e32 v146, s20, v156
	s_cmpk_lg_i32 s14, 0x300
	ds_write_b128 v146, v[222:225]
	ds_write_b128 v146, v[226:229] offset:18432
	ds_write_b128 v146, v[230:233] offset:4608
	ds_write_b128 v146, v[234:237] offset:23040
	ds_write_b128 v146, v[238:241] offset:9216
	ds_write_b128 v146, v[242:245] offset:27648
	ds_write_b128 v146, v[246:249] offset:13824
	ds_write_b128 v146, v[250:253] offset:32256
	s_waitcnt lgkmcnt(0)
	s_barrier
	s_cbranch_scc1 .LBB0_556
	s_and_b32 s20, s19, 1
	s_mul_i32 s21, s20, 0x9000
	s_add_i32 s21, s3, s21
	v_add_u32_e32 v146, s21, v154
	v_add_u32_e32 v147, s21, v155
	ds_read_b128 v[180:183], v146
	ds_read_b128 v[184:187], v146 offset:32
	ds_read_b128 v[188:191], v146 offset:4608
	ds_read_b128 v[192:195], v146 offset:4640
	ds_read_b128 v[200:203], v147 offset:18432
	ds_read_b128 v[210:213], v147 offset:18464
	ds_read_b128 v[214:217], v147 offset:23040
	ds_read_b128 v[218:221], v147 offset:23072
	s_waitcnt lgkmcnt(3)
	v_mfma_f32_32x32x16_bf16 v[52:67], v[180:183], v[200:203], v[52:67]
	s_waitcnt lgkmcnt(1)
	v_mfma_f32_32x32x16_bf16 v[36:51], v[180:183], v[214:217], v[36:51]
	v_mfma_f32_32x32x16_bf16 v[20:35], v[188:191], v[200:203], v[20:35]
	v_mfma_f32_32x32x16_bf16 v[4:19], v[188:191], v[214:217], v[4:19]
	ds_read_b128 v[180:183], v146 offset:64
	ds_read_b128 v[188:191], v146 offset:4672
	ds_read_b128 v[200:203], v147 offset:18496
	ds_read_b128 v[214:217], v147 offset:23104
	v_mfma_f32_32x32x16_bf16 v[52:67], v[184:187], v[210:213], v[52:67]
	s_waitcnt lgkmcnt(4)
	v_mfma_f32_32x32x16_bf16 v[36:51], v[184:187], v[218:221], v[36:51]
	v_mfma_f32_32x32x16_bf16 v[20:35], v[192:195], v[210:213], v[20:35]
	v_mfma_f32_32x32x16_bf16 v[4:19], v[192:195], v[218:221], v[4:19]
	ds_read_b128 v[184:187], v146 offset:96
	ds_read_b128 v[192:195], v146 offset:4704
	ds_read_b128 v[210:213], v147 offset:18528
	ds_read_b128 v[218:221], v147 offset:23136
	s_waitcnt lgkmcnt(5)
	v_mfma_f32_32x32x16_bf16 v[52:67], v[180:183], v[200:203], v[52:67]
	s_waitcnt lgkmcnt(4)
	v_mfma_f32_32x32x16_bf16 v[36:51], v[180:183], v[214:217], v[36:51]
	v_mfma_f32_32x32x16_bf16 v[20:35], v[188:191], v[200:203], v[20:35]
	v_mfma_f32_32x32x16_bf16 v[4:19], v[188:191], v[214:217], v[4:19]
	s_waitcnt lgkmcnt(1)
	v_mfma_f32_32x32x16_bf16 v[52:67], v[184:187], v[210:213], v[52:67]
	s_waitcnt lgkmcnt(0)
	v_mfma_f32_32x32x16_bf16 v[36:51], v[184:187], v[218:221], v[36:51]
	v_mfma_f32_32x32x16_bf16 v[20:35], v[192:195], v[210:213], v[20:35]
	v_mfma_f32_32x32x16_bf16 v[4:19], v[192:195], v[218:221], v[4:19]
	s_xor_b32 s20, s20, 1
	s_add_i32 s19, s19, 1
	s_add_u32 s14, s14, 0x80
	s_mul_i32 s20, s20, 0x9000
	s_addc_u32 s15, s15, 0
	s_barrier
	s_waitcnt vmcnt(0)
	v_add_u32_e32 v146, s20, v156
	ds_write_b128 v146, v[138:141]
	ds_write_b128 v146, v[142:145] offset:18432
	ds_write_b128 v146, v[150:153] offset:4608
	ds_write_b128 v146, v[158:161] offset:23040
	ds_write_b128 v146, v[162:165] offset:9216
	ds_write_b128 v146, v[168:171] offset:27648
	ds_write_b128 v146, v[172:175] offset:13824
	ds_write_b128 v146, v[176:179] offset:32256
	s_waitcnt lgkmcnt(0)
	s_barrier
	v_add_u32_e32 v146, s3, v154
	v_add_u32_e32 v147, s3, v155
	ds_read_b128 v[134:137], v146 offset:36864
	ds_read_b128 v[138:141], v146 offset:36896
	ds_read_b128 v[142:145], v146 offset:41472
	ds_read_b128 v[150:153], v146 offset:41504
	ds_read_b128 v[154:157], v147 offset:55296
	ds_read_b128 v[158:161], v147 offset:55328
	ds_read_b128 v[162:165], v147 offset:59904
	ds_read_b128 v[168:171], v147 offset:59936
	s_waitcnt lgkmcnt(3)
	v_mfma_f32_32x32x16_bf16 v[52:67], v[134:137], v[154:157], v[52:67]
	s_waitcnt lgkmcnt(1)
	v_mfma_f32_32x32x16_bf16 v[36:51], v[134:137], v[162:165], v[36:51]
	v_mfma_f32_32x32x16_bf16 v[20:35], v[142:145], v[154:157], v[20:35]
	v_mfma_f32_32x32x16_bf16 v[4:19], v[142:145], v[162:165], v[4:19]
	ds_read_b128 v[134:137], v146 offset:36928
	ds_read_b128 v[142:145], v146 offset:41536
	ds_read_b128 v[154:157], v147 offset:55360
	ds_read_b128 v[162:165], v147 offset:59968
	v_mfma_f32_32x32x16_bf16 v[52:67], v[138:141], v[158:161], v[52:67]
	s_waitcnt lgkmcnt(4)
	v_mfma_f32_32x32x16_bf16 v[36:51], v[138:141], v[168:171], v[36:51]
	v_mfma_f32_32x32x16_bf16 v[20:35], v[150:153], v[158:161], v[20:35]
	v_mfma_f32_32x32x16_bf16 v[4:19], v[150:153], v[168:171], v[4:19]
	ds_read_b128 v[138:141], v146 offset:36960
	ds_read_b128 v[150:153], v146 offset:41568
	ds_read_b128 v[158:161], v147 offset:55392
	ds_read_b128 v[168:171], v147 offset:60000
	s_waitcnt lgkmcnt(5)
	v_mfma_f32_32x32x16_bf16 v[52:67], v[134:137], v[154:157], v[52:67]
	s_waitcnt lgkmcnt(4)
	v_mfma_f32_32x32x16_bf16 v[36:51], v[134:137], v[162:165], v[36:51]
	v_mfma_f32_32x32x16_bf16 v[20:35], v[142:145], v[154:157], v[20:35]
	v_mfma_f32_32x32x16_bf16 v[4:19], v[142:145], v[162:165], v[4:19]
	s_waitcnt lgkmcnt(1)
	v_mfma_f32_32x32x16_bf16 v[52:67], v[138:141], v[158:161], v[52:67]
	s_mov_b64 s[14:15], -1
	s_and_b64 vcc, exec, s[12:13]
	s_waitcnt lgkmcnt(0)
	s_barrier
	v_mfma_f32_32x32x16_bf16 v[36:51], v[138:141], v[168:171], v[36:51]
	v_mfma_f32_32x32x16_bf16 v[20:35], v[150:153], v[158:161], v[20:35]
	v_mfma_f32_32x32x16_bf16 v[4:19], v[150:153], v[168:171], v[4:19]
	s_cbranch_vccz .LBB0_559
	s_load_dwordx2 s[12:13], s[0:1], 0x170
	s_add_i32 s84, s5, -1
	s_lshl_b64 s[14:15], s[84:85], 26
	s_waitcnt lgkmcnt(0)
	s_add_u32 s12, s12, s14
	s_addc_u32 s13, s13, s15
	s_mov_b64 s[14:15], 0
